# P8 gate epilogue: -log2e folded into the per-row rms scale (127 v_mul fewer per lane per tile)
# speedup vs baseline: 1.0047x; 1.0047x over previous
; DI float sigmoidf_(float x) { return 1.0f / (1.0f + __expf(-x)); }
; DI void unpack8(const u32x4 w, float (&f)[8]) { f[0] = bflo(w.x); f[1] = bfhi(w.x); f[2] = bflo(w.y); f[3] = bfhi(w.y); f[4] = bflo(w.z); f[5] = bfhi(w.z); f[6] = bflo(w.w); f[7] = bfhi(w.w); }
; DI u32x4 pack8(const float (&f)[8]) { u32x4 w; w.x = pk2(f[0], f[1]); w.y = pk2(f[2], f[3]); w.z = pk2(f[4], f[5]); w.w = pk2(f[6], f[7]); return w; }
; DI float rscale(const float* ss, int row) { const unsigned long long v = ((const unsigned long long*)ss)[row]; return rsqrtf((float)v * (1.0f / SS_FIX) * (1.f / 1024.f) + EPS); }
;     __device__ __forceinline__ void operator()(const f32x4 (&acc)[2][2][4][2], const pg8::Unit& u, int wr, int wc, int fr, int fq) const {
;     ...
;             u32x4 ov[4][2], sv[4][2]; float rc[4];
; #pragma unroll
;             for (int m = 0; m < 4; ++m) {
;                 const int row = row0 + ai * pg8::HALF + m * 16;
; #pragma unroll
;                 for (int bj = 0; bj < 2; ++bj) {
;                     const int col = col0 + bj * pg8::HALF;
;                     ov[m][bj] = *(const u32x4*)(P + (size_t)row * ldc + col);
;                     sv[m][bj] = (u32x4){0, 0, 0, 0};
;                     if (mix) sv[m][bj] = *(const u32x4*)(P + (size_t)row * ldc + (col & 1023));
;                 }
;                 rc[m] = rscale(ss, row);
;             }
; #pragma unroll
;             for (int m = 0; m < 4; ++m) {
;                 const int row = row0 + ai * pg8::HALF + m * 16;
; #pragma unroll
;                 for (int bj = 0; bj < 2; ++bj) {
;                     const int col = col0 + bj * pg8::HALF;
;                     const f32x4 a = acc[ai][bj][m][0] * rc[m], b = acc[ai][bj][m][1] * rc[m];
;                     float o[8], s[8]; unpack8(ov[m][bj], o); unpack8(sv[m][bj], s);
;                     s[0] += sigmoidf_(a[0]) * o[0]; s[1] += sigmoidf_(a[1]) * o[1]; s[2] += sigmoidf_(a[2]) * o[2]; s[3] += sigmoidf_(a[3]) * o[3];
;                     s[4] += sigmoidf_(b[0]) * o[4]; s[5] += sigmoidf_(b[1]) * o[5]; s[6] += sigmoidf_(b[2]) * o[6]; s[7] += sigmoidf_(b[3]) * o[7];
;                     *(u32x4*)(P + (size_t)row * ldc + (col & 1023)) = pack8(s);
;                 }
.LBB0_1382:
	v_ashrrev_i32_e32 v225, 31, v224
	v_lshl_add_u64 v[224:225], v[224:225], 3, s[20:21]
	global_load_dwordx2 v[224:225], v[224:225], off
	s_waitcnt vmcnt(0)
	v_ffbh_u32_e32 v219, v229
	v_min_u32_e32 v219, 32, v219
	v_lshlrev_b64 v[228:229], v219, v[228:229]
	v_min_u32_e32 v221, 1, v228
	v_or_b32_e32 v221, v229, v221
	v_cvt_f32_u32_e32 v221, v221
	v_sub_u32_e32 v219, 32, v219
	v_ldexp_f32 v219, v221, v219
	v_mul_f32_e32 v219, 0x33800000, v219
	v_fmamk_f32 v219, v219, 0x3a800000, v247
	v_cmp_gt_f32_e32 vcc, s59, v219
	v_mul_f32_e32 v221, 0x4b800000, v219
	s_nop 0
	v_cndmask_b32_e32 v219, v219, v221, vcc
	v_rsq_f32_e32 v219, v219
	s_nop 0
	v_mul_f32_e32 v221, 0x45800000, v219
	v_cndmask_b32_e32 v228, v219, v221, vcc
	v_mul_f32_e32 v228, 0xbfb8aa3b, v228
	v_ffbh_u32_e32 v219, v233
	v_min_u32_e32 v219, 32, v219
	v_lshlrev_b64 v[232:233], v219, v[232:233]
	v_min_u32_e32 v221, 1, v232
	v_or_b32_e32 v221, v233, v221
	v_cvt_f32_u32_e32 v221, v221
	v_sub_u32_e32 v219, 32, v219
	v_ldexp_f32 v219, v221, v219
	v_mul_f32_e32 v219, 0x33800000, v219
	v_fmamk_f32 v219, v219, 0x3a800000, v247
	v_cmp_gt_f32_e32 vcc, s59, v219
	v_mul_f32_e32 v221, 0x4b800000, v219
	s_nop 0
	v_cndmask_b32_e32 v219, v219, v221, vcc
	v_rsq_f32_e32 v219, v219
	s_nop 0
	v_mul_f32_e32 v221, 0x45800000, v219
	v_cndmask_b32_e32 v232, v219, v221, vcc
	v_mul_f32_e32 v232, 0xbfb8aa3b, v232
	v_ffbh_u32_e32 v219, v237
	v_min_u32_e32 v219, 32, v219
	v_lshlrev_b64 v[236:237], v219, v[236:237]
	v_min_u32_e32 v221, 1, v236
	v_or_b32_e32 v221, v237, v221
	v_cvt_f32_u32_e32 v221, v221
	v_sub_u32_e32 v219, 32, v219
	v_ldexp_f32 v219, v221, v219
	v_mul_f32_e32 v219, 0x33800000, v219
	v_fmamk_f32 v219, v219, 0x3a800000, v247
	v_cmp_gt_f32_e32 vcc, s59, v219
	v_mul_f32_e32 v221, 0x4b800000, v219
	s_nop 0
	v_cndmask_b32_e32 v219, v219, v221, vcc
	v_rsq_f32_e32 v219, v219
	s_nop 0
	v_mul_f32_e32 v221, 0x45800000, v219
	v_cndmask_b32_e32 v236, v219, v221, vcc
	v_mul_f32_e32 v236, 0xbfb8aa3b, v236
	v_pk_mul_f32 v[240:241], v[178:179], v[236:237] op_sel_hi:[1,0]
	v_pk_mul_f32 v[238:239], v[180:181], v[236:237] op_sel_hi:[1,0]
	v_pk_mul_f32 v[180:181], v[182:183], v[236:237] op_sel_hi:[1,0]
	v_exp_f32_e32 v240, v240
	v_exp_f32_e32 v241, v241
	v_lshlrev_b32_e32 v182, 16, v186
	v_and_b32_e32 v183, 0xffff0000, v186
	v_pk_mul_f32 v[178:179], v[184:185], v[236:237] op_sel_hi:[1,0]
	v_pk_add_f32 v[240:241], v[240:241], 1.0 op_sel_hi:[1,0]
	v_lshlrev_b32_e32 v184, 16, v190
	v_ffbh_u32_e32 v219, v225
	v_min_u32_e32 v219, 32, v219
	v_lshlrev_b64 v[224:225], v219, v[224:225]
	v_min_u32_e32 v221, 1, v224
	v_or_b32_e32 v221, v225, v221
	v_cvt_f32_u32_e32 v221, v221
	v_sub_u32_e32 v219, 32, v219
	v_and_b32_e32 v185, 0xffff0000, v190
	v_ldexp_f32 v219, v221, v219
	v_mul_f32_e32 v219, 0x33800000, v219
	v_fmamk_f32 v219, v219, 0x3a800000, v247
	v_cmp_gt_f32_e32 vcc, s59, v219
	v_mul_f32_e32 v221, 0x4b800000, v219
	s_nop 1
	v_cndmask_b32_e32 v219, v219, v221, vcc
	v_rsq_f32_e32 v219, v219
	v_exp_f32_e32 v180, v180
	v_exp_f32_e32 v181, v181
	v_mul_f32_e32 v221, 0x45800000, v219
	v_cndmask_b32_e32 v224, v219, v221, vcc
	v_mul_f32_e32 v224, 0xbfb8aa3b, v224
	v_rcp_f32_e32 v241, v241
	v_pk_add_f32 v[180:181], v[180:181], 1.0 op_sel_hi:[1,0]
	v_rcp_f32_e32 v240, v240
	s_nop 0
	v_pk_fma_f32 v[182:183], v[240:241], v[182:183], v[184:185]
	v_exp_f32_e32 v184, v238
	v_exp_f32_e32 v185, v239
	v_lshlrev_b32_e32 v186, 16, v187
	v_and_b32_e32 v187, 0xffff0000, v187
	v_lshlrev_b32_e32 v190, 16, v191
	v_pk_add_f32 v[184:185], v[184:185], 1.0 op_sel_hi:[1,0]
	v_and_b32_e32 v191, 0xffff0000, v191
	v_exp_f32_e32 v178, v178
	v_exp_f32_e32 v179, v179
	v_pk_mul_f32 v[158:159], v[158:159], v[236:237] op_sel_hi:[1,0]
	v_rcp_f32_e32 v185, v185
	v_pk_add_f32 v[178:179], v[178:179], 1.0 op_sel_hi:[1,0]
	v_pk_mul_f32 v[160:161], v[160:161], v[236:237] op_sel_hi:[1,0]
	v_pk_mul_f32 v[156:157], v[156:157], v[236:237] op_sel_hi:[1,0]
	v_rcp_f32_e32 v184, v184
	s_nop 0
	v_pk_fma_f32 v[184:185], v[184:185], v[186:187], v[190:191]
	v_lshlrev_b32_e32 v186, 16, v188
	v_and_b32_e32 v187, 0xffff0000, v188
	v_lshlrev_b32_e32 v190, 16, v192
	v_and_b32_e32 v191, 0xffff0000, v192
	v_exp_f32_e32 v156, v156
	v_rcp_f32_e32 v181, v181
	v_exp_f32_e32 v157, v157
	v_pk_mul_f32 v[142:143], v[142:143], v[232:233] op_sel_hi:[1,0]
	v_pk_mul_f32 v[144:145], v[144:145], v[232:233] op_sel_hi:[1,0]
	v_rcp_f32_e32 v180, v180
	s_nop 0
	v_pk_fma_f32 v[186:187], v[180:181], v[186:187], v[190:191]
	v_lshlrev_b32_e32 v180, 16, v189
	v_and_b32_e32 v181, 0xffff0000, v189
	v_lshlrev_b32_e32 v188, 16, v193
	v_and_b32_e32 v189, 0xffff0000, v193
	v_rcp_f32_e32 v179, v179
	v_pk_add_f32 v[156:157], v[156:157], 1.0 op_sel_hi:[1,0]
	v_pk_mul_f32 v[140:141], v[140:141], v[232:233] op_sel_hi:[1,0]
	v_pk_mul_f32 v[126:127], v[126:127], v[232:233] op_sel_hi:[1,0]
	v_rcp_f32_e32 v178, v178
	s_nop 0
	v_pk_fma_f32 v[178:179], v[178:179], v[180:181], v[188:189]
	v_cvt_pk_bf16_f32 v180, v182, v183
	v_cvt_pk_bf16_f32 v181, v184, v185
	v_cvt_pk_bf16_f32 v182, v186, v187
	v_cvt_pk_bf16_f32 v183, v178, v179
	v_lshl_add_u64 v[178:179], v[234:235], 0, v[0:1]
	global_store_dwordx4 v[178:179], v[180:183], off
	s_nop 1
	v_pk_mul_f32 v[180:181], v[154:155], v[236:237] op_sel_hi:[1,0]
	v_exp_f32_e32 v154, v158
	v_exp_f32_e32 v155, v159
	v_lshlrev_b32_e32 v182, 16, v170
	v_and_b32_e32 v183, 0xffff0000, v170
	v_lshlrev_b32_e32 v158, 16, v174
	v_pk_add_f32 v[154:155], v[154:155], 1.0 op_sel_hi:[1,0]
	v_and_b32_e32 v159, 0xffff0000, v174
	v_exp_f32_e32 v140, v140
	v_exp_f32_e32 v141, v141
	v_pk_mul_f32 v[128:129], v[128:129], v[232:233] op_sel_hi:[1,0]
	v_rcp_f32_e32 v155, v155
; DI float sigmoidf_(float x) { return 1.0f / (1.0f + __expf(-x)); }
; DI void unpack8(const u32x4 w, float (&f)[8]) { f[0] = bflo(w.x); f[1] = bfhi(w.x); f[2] = bflo(w.y); f[3] = bfhi(w.y); f[4] = bflo(w.z); f[5] = bfhi(w.z); f[6] = bflo(w.w); f[7] = bfhi(w.w); }
; DI u32x4 pack8(const float (&f)[8]) { u32x4 w; w.x = pk2(f[0], f[1]); w.y = pk2(f[2], f[3]); w.z = pk2(f[4], f[5]); w.w = pk2(f[6], f[7]); return w; }
;     __device__ __forceinline__ void operator()(const f32x4 (&acc)[2][2][4][2], const pg8::Unit& u, int wr, int wc, int fr, int fq) const {
;     ...
;             for (int m = 0; m < 4; ++m) {
;                 const int row = row0 + ai * pg8::HALF + m * 16;
; #pragma unroll
;                 for (int bj = 0; bj < 2; ++bj) {
;                     const int col = col0 + bj * pg8::HALF;
;                     const f32x4 a = acc[ai][bj][m][0] * rc[m], b = acc[ai][bj][m][1] * rc[m];
;                     float o[8], s[8]; unpack8(ov[m][bj], o); unpack8(sv[m][bj], s);
;                     s[0] += sigmoidf_(a[0]) * o[0]; s[1] += sigmoidf_(a[1]) * o[1]; s[2] += sigmoidf_(a[2]) * o[2]; s[3] += sigmoidf_(a[3]) * o[3];
;                     s[4] += sigmoidf_(b[0]) * o[4]; s[5] += sigmoidf_(b[1]) * o[5]; s[6] += sigmoidf_(b[2]) * o[6]; s[7] += sigmoidf_(b[3]) * o[7];
;                     *(u32x4*)(P + (size_t)row * ldc + (col & 1023)) = pack8(s);
;                 }
	v_pk_add_f32 v[140:141], v[140:141], 1.0 op_sel_hi:[1,0]
	v_pk_mul_f32 v[124:125], v[124:125], v[232:233] op_sel_hi:[1,0]
	v_pk_mul_f32 v[102:103], v[102:103], v[228:229] op_sel_hi:[1,0]
	v_rcp_f32_e32 v154, v154
	s_nop 0
	v_pk_fma_f32 v[154:155], v[154:155], v[158:159], v[182:183]
	v_exp_f32_e32 v158, v160
	v_exp_f32_e32 v159, v161
	v_lshlrev_b32_e32 v160, 16, v175
	v_and_b32_e32 v161, 0xffff0000, v175
	v_lshlrev_b32_e32 v170, 16, v171
	v_pk_add_f32 v[158:159], v[158:159], 1.0 op_sel_hi:[1,0]
	v_and_b32_e32 v171, 0xffff0000, v171
	v_cvt_pk_bf16_f32 v154, v154, v155
	v_rcp_f32_e32 v159, v159
	v_exp_f32_e32 v124, v124
	v_exp_f32_e32 v125, v125
	v_pk_mul_f32 v[104:105], v[104:105], v[228:229] op_sel_hi:[1,0]
	v_rcp_f32_e32 v158, v158
	s_nop 0
	v_pk_fma_f32 v[158:159], v[158:159], v[160:161], v[170:171]
	v_exp_f32_e32 v160, v180
	v_exp_f32_e32 v161, v181
	v_lshlrev_b32_e32 v174, 16, v172
	v_and_b32_e32 v175, 0xffff0000, v172
	v_lshlrev_b32_e32 v170, 16, v176
	v_pk_add_f32 v[160:161], v[160:161], 1.0 op_sel_hi:[1,0]
	v_and_b32_e32 v171, 0xffff0000, v176
	v_cvt_pk_bf16_f32 v155, v158, v159
	v_pk_add_f32 v[124:125], v[124:125], 1.0 op_sel_hi:[1,0]
	v_pk_mul_f32 v[100:101], v[100:101], v[228:229] op_sel_hi:[1,0]
	v_rcp_f32_e32 v161, v161
	v_exp_f32_e32 v100, v100
	v_rcp_f32_e32 v160, v160
	s_nop 0
	v_pk_fma_f32 v[160:161], v[160:161], v[170:171], v[174:175]
	v_lshlrev_b32_e32 v170, 16, v177
	v_and_b32_e32 v171, 0xffff0000, v177
	v_lshlrev_b32_e32 v172, 16, v173
	v_rcp_f32_e32 v157, v157
	v_and_b32_e32 v173, 0xffff0000, v173
	v_exp_f32_e32 v101, v101
	v_pk_mul_f32 v[86:87], v[86:87], v[228:229] op_sel_hi:[1,0]
	v_rcp_f32_e32 v156, v156
	s_nop 0
	v_pk_fma_f32 v[170:171], v[156:157], v[170:171], v[172:173]
	v_cvt_pk_bf16_f32 v156, v160, v161
	v_cvt_pk_bf16_f32 v157, v170, v171
	global_store_dwordx4 v[178:179], v[154:157], off offset:256
	v_pk_add_f32 v[100:101], v[100:101], 1.0 op_sel_hi:[1,0]
	v_pk_mul_f32 v[88:89], v[88:89], v[228:229] op_sel_hi:[1,0]
	v_pk_mul_f32 v[154:155], v[138:139], v[232:233] op_sel_hi:[1,0]
	v_exp_f32_e32 v138, v142
	v_exp_f32_e32 v139, v143
	v_lshlrev_b32_e32 v142, 16, v162
	v_and_b32_e32 v143, 0xffff0000, v162
	v_lshlrev_b32_e32 v156, 16, v166
	v_pk_add_f32 v[138:139], v[138:139], 1.0 op_sel_hi:[1,0]
	v_and_b32_e32 v157, 0xffff0000, v166
	v_pk_mul_f32 v[84:85], v[84:85], v[228:229] op_sel_hi:[1,0]
	v_pk_mul_f32 v[78:79], v[78:79], v[224:225] op_sel_hi:[1,0]
	v_rcp_f32_e32 v139, v139
	v_exp_f32_e32 v84, v84
	v_exp_f32_e32 v85, v85
	v_rcp_f32_e32 v138, v138
	s_nop 0
	v_pk_fma_f32 v[138:139], v[138:139], v[142:143], v[156:157]
	v_exp_f32_e32 v142, v144
	v_exp_f32_e32 v143, v145
	v_lshlrev_b32_e32 v144, 16, v163
	v_and_b32_e32 v145, 0xffff0000, v163
	v_lshlrev_b32_e32 v156, 16, v167
	v_pk_add_f32 v[142:143], v[142:143], 1.0 op_sel_hi:[1,0]
	v_and_b32_e32 v157, 0xffff0000, v167
	v_pk_add_f32 v[84:85], v[84:85], 1.0 op_sel_hi:[1,0]
	v_pk_mul_f32 v[80:81], v[80:81], v[224:225] op_sel_hi:[1,0]
	v_pk_mul_f32 v[76:77], v[76:77], v[224:225] op_sel_hi:[1,0]
	v_rcp_f32_e32 v143, v143
	v_exp_f32_e32 v76, v76
	v_rcp_f32_e32 v142, v142
	s_nop 0
	v_pk_fma_f32 v[142:143], v[142:143], v[144:145], v[156:157]
	v_exp_f32_e32 v144, v154
	v_exp_f32_e32 v145, v155
	v_lshlrev_b32_e32 v154, 16, v164
	v_and_b32_e32 v155, 0xffff0000, v164
	v_lshlrev_b32_e32 v156, 16, v168
	v_pk_add_f32 v[144:145], v[144:145], 1.0 op_sel_hi:[1,0]
	v_and_b32_e32 v157, 0xffff0000, v168
	v_exp_f32_e32 v77, v77
	v_pk_mul_f32 v[70:71], v[70:71], v[224:225] op_sel_hi:[1,0]
	v_pk_mul_f32 v[72:73], v[72:73], v[224:225] op_sel_hi:[1,0]
	v_rcp_f32_e32 v145, v145
	v_pk_add_f32 v[76:77], v[76:77], 1.0 op_sel_hi:[1,0]
	v_pk_mul_f32 v[68:69], v[68:69], v[224:225] op_sel_hi:[1,0]
	v_rcp_f32_e32 v144, v144
	s_nop 0
	v_pk_fma_f32 v[144:145], v[144:145], v[154:155], v[156:157]
	v_lshlrev_b32_e32 v154, 16, v165
	v_and_b32_e32 v155, 0xffff0000, v165
	v_rcp_f32_e32 v141, v141
	v_lshlrev_b32_e32 v156, 16, v169
	v_and_b32_e32 v157, 0xffff0000, v169
	v_rcp_f32_e32 v140, v140
	s_nop 0
	v_pk_fma_f32 v[154:155], v[140:141], v[154:155], v[156:157]
	v_cvt_pk_bf16_f32 v140, v138, v139
	v_cvt_pk_bf16_f32 v141, v142, v143
	v_cvt_pk_bf16_f32 v142, v144, v145
	v_cvt_pk_bf16_f32 v143, v154, v155
	v_lshl_add_u64 v[138:139], v[230:231], 0, v[0:1]
	global_store_dwordx4 v[138:139], v[140:143], off
	v_exp_f32_e32 v68, v68
	s_nop 1
	v_pk_mul_f32 v[140:141], v[122:123], v[232:233] op_sel_hi:[1,0]
	v_exp_f32_e32 v122, v126
	v_exp_f32_e32 v123, v127
	v_lshlrev_b32_e32 v142, 16, v146
	v_and_b32_e32 v143, 0xffff0000, v146
	v_lshlrev_b32_e32 v126, 16, v150
	v_pk_add_f32 v[122:123], v[122:123], 1.0 op_sel_hi:[1,0]
	v_and_b32_e32 v127, 0xffff0000, v150
	v_exp_f32_e32 v69, v69
	v_rcp_f32_e32 v123, v123
	v_pk_add_f32 v[68:69], v[68:69], 1.0 op_sel_hi:[1,0]
	v_rcp_f32_e32 v122, v122
	s_nop 0
	v_pk_fma_f32 v[122:123], v[122:123], v[126:127], v[142:143]
	v_exp_f32_e32 v126, v128
	v_exp_f32_e32 v127, v129
	v_lshlrev_b32_e32 v142, 16, v147
	v_and_b32_e32 v143, 0xffff0000, v147
	v_lshlrev_b32_e32 v128, 16, v151
	v_pk_add_f32 v[126:127], v[126:127], 1.0 op_sel_hi:[1,0]
	v_and_b32_e32 v129, 0xffff0000, v151
	v_cvt_pk_bf16_f32 v122, v122, v123
	v_rcp_f32_e32 v127, v127
	s_nop 0
	v_rcp_f32_e32 v126, v126
	s_nop 0
	v_pk_fma_f32 v[126:127], v[126:127], v[128:129], v[142:143]
	v_exp_f32_e32 v128, v140
	v_exp_f32_e32 v129, v141
	v_lshlrev_b32_e32 v142, 16, v148
	v_and_b32_e32 v143, 0xffff0000, v148
	v_lshlrev_b32_e32 v140, 16, v152
	v_pk_add_f32 v[128:129], v[128:129], 1.0 op_sel_hi:[1,0]
	v_and_b32_e32 v141, 0xffff0000, v152
	v_cvt_pk_bf16_f32 v123, v126, v127
	v_rcp_f32_e32 v129, v129
	s_nop 0
	v_rcp_f32_e32 v128, v128
; DI float sigmoidf_(float x) { return 1.0f / (1.0f + __expf(-x)); }
; DI void unpack8(const u32x4 w, float (&f)[8]) { f[0] = bflo(w.x); f[1] = bfhi(w.x); f[2] = bflo(w.y); f[3] = bfhi(w.y); f[4] = bflo(w.z); f[5] = bfhi(w.z); f[6] = bflo(w.w); f[7] = bfhi(w.w); }
; DI u32x4 pack8(const float (&f)[8]) { u32x4 w; w.x = pk2(f[0], f[1]); w.y = pk2(f[2], f[3]); w.z = pk2(f[4], f[5]); w.w = pk2(f[6], f[7]); return w; }
;     __device__ __forceinline__ void operator()(const f32x4 (&acc)[2][2][4][2], const pg8::Unit& u, int wr, int wc, int fr, int fq) const {
;     ...
;             for (int m = 0; m < 4; ++m) {
;                 const int row = row0 + ai * pg8::HALF + m * 16;
; #pragma unroll
;                 for (int bj = 0; bj < 2; ++bj) {
;                     const int col = col0 + bj * pg8::HALF;
;                     const f32x4 a = acc[ai][bj][m][0] * rc[m], b = acc[ai][bj][m][1] * rc[m];
;                     float o[8], s[8]; unpack8(ov[m][bj], o); unpack8(sv[m][bj], s);
;                     s[0] += sigmoidf_(a[0]) * o[0]; s[1] += sigmoidf_(a[1]) * o[1]; s[2] += sigmoidf_(a[2]) * o[2]; s[3] += sigmoidf_(a[3]) * o[3];
;                     s[4] += sigmoidf_(b[0]) * o[4]; s[5] += sigmoidf_(b[1]) * o[5]; s[6] += sigmoidf_(b[2]) * o[6]; s[7] += sigmoidf_(b[3]) * o[7];
;                     *(u32x4*)(P + (size_t)row * ldc + (col & 1023)) = pack8(s);
;                 }
	s_nop 0
	v_pk_fma_f32 v[128:129], v[128:129], v[140:141], v[142:143]
	v_lshlrev_b32_e32 v140, 16, v153
	v_and_b32_e32 v141, 0xffff0000, v153
	v_rcp_f32_e32 v125, v125
	v_lshlrev_b32_e32 v142, 16, v149
	v_and_b32_e32 v143, 0xffff0000, v149
	v_rcp_f32_e32 v124, v124
	s_nop 0
	v_pk_fma_f32 v[140:141], v[124:125], v[140:141], v[142:143]
	v_cvt_pk_bf16_f32 v124, v128, v129
	v_cvt_pk_bf16_f32 v125, v140, v141
	global_store_dwordx4 v[138:139], v[122:125], off offset:256
	s_nop 1
	v_pk_mul_f32 v[122:123], v[98:99], v[228:229] op_sel_hi:[1,0]
	v_exp_f32_e32 v98, v102
	v_exp_f32_e32 v99, v103
	v_lshlrev_b32_e32 v102, 16, v130
	v_and_b32_e32 v103, 0xffff0000, v130
	v_lshlrev_b32_e32 v124, 16, v134
	v_pk_add_f32 v[98:99], v[98:99], 1.0 op_sel_hi:[1,0]
	v_and_b32_e32 v125, 0xffff0000, v134
	s_nop 0
	v_rcp_f32_e32 v99, v99
	s_nop 0
	v_rcp_f32_e32 v98, v98
	s_nop 0
	v_pk_fma_f32 v[98:99], v[98:99], v[102:103], v[124:125]
	v_exp_f32_e32 v102, v104
	v_exp_f32_e32 v103, v105
	v_lshlrev_b32_e32 v104, 16, v131
	v_and_b32_e32 v105, 0xffff0000, v131
	v_lshlrev_b32_e32 v124, 16, v135
	v_pk_add_f32 v[102:103], v[102:103], 1.0 op_sel_hi:[1,0]
	v_and_b32_e32 v125, 0xffff0000, v135
	s_nop 0
	v_rcp_f32_e32 v103, v103
	s_nop 0
	v_rcp_f32_e32 v102, v102
	s_nop 0
	v_pk_fma_f32 v[102:103], v[102:103], v[104:105], v[124:125]
	v_exp_f32_e32 v104, v122
	v_exp_f32_e32 v105, v123
	v_lshlrev_b32_e32 v122, 16, v132
	v_and_b32_e32 v123, 0xffff0000, v132
	v_lshlrev_b32_e32 v124, 16, v136
	v_pk_add_f32 v[104:105], v[104:105], 1.0 op_sel_hi:[1,0]
	v_and_b32_e32 v125, 0xffff0000, v136
	s_nop 0
	v_rcp_f32_e32 v105, v105
	s_nop 0
	v_rcp_f32_e32 v104, v104
	s_nop 0
	v_pk_fma_f32 v[104:105], v[104:105], v[122:123], v[124:125]
	v_lshlrev_b32_e32 v122, 16, v133
	v_and_b32_e32 v123, 0xffff0000, v133
	v_rcp_f32_e32 v101, v101
	v_lshlrev_b32_e32 v124, 16, v137
	v_and_b32_e32 v125, 0xffff0000, v137
	v_rcp_f32_e32 v100, v100
	s_nop 0
	v_pk_fma_f32 v[122:123], v[100:101], v[122:123], v[124:125]
	v_cvt_pk_bf16_f32 v100, v98, v99
	v_cvt_pk_bf16_f32 v101, v102, v103
	v_cvt_pk_bf16_f32 v102, v104, v105
	v_cvt_pk_bf16_f32 v103, v122, v123
	v_lshl_add_u64 v[98:99], v[226:227], 0, v[0:1]
	global_store_dwordx4 v[98:99], v[100:103], off
	v_mov_b32_e32 v126, 0
	v_mov_b32_e32 v127, 0
	v_pk_mul_f32 v[100:101], v[82:83], v[228:229] op_sel_hi:[1,0]
	v_exp_f32_e32 v82, v86
	v_exp_f32_e32 v83, v87
	v_lshlrev_b32_e32 v102, 16, v114
	v_and_b32_e32 v103, 0xffff0000, v114
	v_lshlrev_b32_e32 v86, 16, v118
	v_pk_add_f32 v[82:83], v[82:83], 1.0 op_sel_hi:[1,0]
	v_and_b32_e32 v87, 0xffff0000, v118
	v_mov_b32_e32 v128, 0
	v_mov_b32_e32 v129, 0
	v_rcp_f32_e32 v83, v83
	s_nop 0
	v_rcp_f32_e32 v82, v82
	s_nop 0
	v_pk_fma_f32 v[82:83], v[82:83], v[86:87], v[102:103]
	v_exp_f32_e32 v86, v88
	v_exp_f32_e32 v87, v89
	v_lshlrev_b32_e32 v102, 16, v115
	v_and_b32_e32 v103, 0xffff0000, v115
	v_lshlrev_b32_e32 v88, 16, v119
	v_pk_add_f32 v[86:87], v[86:87], 1.0 op_sel_hi:[1,0]
	v_and_b32_e32 v89, 0xffff0000, v119
	v_cvt_pk_bf16_f32 v82, v82, v83
	v_rcp_f32_e32 v87, v87
	s_nop 0
	v_rcp_f32_e32 v86, v86
	s_nop 0
	v_pk_fma_f32 v[86:87], v[86:87], v[88:89], v[102:103]
	v_exp_f32_e32 v88, v100
	v_exp_f32_e32 v89, v101
	v_lshlrev_b32_e32 v102, 16, v116
	v_and_b32_e32 v103, 0xffff0000, v116
	v_lshlrev_b32_e32 v100, 16, v120
	v_pk_add_f32 v[88:89], v[88:89], 1.0 op_sel_hi:[1,0]
	v_and_b32_e32 v101, 0xffff0000, v120
	v_cvt_pk_bf16_f32 v83, v86, v87
	v_rcp_f32_e32 v89, v89
	s_nop 0
	v_rcp_f32_e32 v88, v88
	s_nop 0
	v_pk_fma_f32 v[88:89], v[88:89], v[100:101], v[102:103]
	v_lshlrev_b32_e32 v100, 16, v121
	v_and_b32_e32 v101, 0xffff0000, v121
	v_rcp_f32_e32 v85, v85
	v_lshlrev_b32_e32 v102, 16, v117
	v_and_b32_e32 v103, 0xffff0000, v117
	v_rcp_f32_e32 v84, v84
	s_nop 0
	v_pk_fma_f32 v[100:101], v[84:85], v[100:101], v[102:103]
; DI float sigmoidf_(float x) { return 1.0f / (1.0f + __expf(-x)); }
; DI void unpack8(const u32x4 w, float (&f)[8]) { f[0] = bflo(w.x); f[1] = bfhi(w.x); f[2] = bflo(w.y); f[3] = bfhi(w.y); f[4] = bflo(w.z); f[5] = bfhi(w.z); f[6] = bflo(w.w); f[7] = bfhi(w.w); }
; DI u32x4 pack8(const float (&f)[8]) { u32x4 w; w.x = pk2(f[0], f[1]); w.y = pk2(f[2], f[3]); w.z = pk2(f[4], f[5]); w.w = pk2(f[6], f[7]); return w; }
;     __device__ __forceinline__ void operator()(const f32x4 (&acc)[2][2][4][2], const pg8::Unit& u, int wr, int wc, int fr, int fq) const {
;     ...
;                     ov[m][bj] = *(const u32x4*)(P + (size_t)row * ldc + col);
;                     sv[m][bj] = (u32x4){0, 0, 0, 0};
;                     if (mix) sv[m][bj] = *(const u32x4*)(P + (size_t)row * ldc + (col & 1023));
;     ...
;             for (int m = 0; m < 4; ++m) {
;                 const int row = row0 + ai * pg8::HALF + m * 16;
; #pragma unroll
;                 for (int bj = 0; bj < 2; ++bj) {
;                     const int col = col0 + bj * pg8::HALF;
;                     const f32x4 a = acc[ai][bj][m][0] * rc[m], b = acc[ai][bj][m][1] * rc[m];
;                     float o[8], s[8]; unpack8(ov[m][bj], o); unpack8(sv[m][bj], s);
;                     s[0] += sigmoidf_(a[0]) * o[0]; s[1] += sigmoidf_(a[1]) * o[1]; s[2] += sigmoidf_(a[2]) * o[2]; s[3] += sigmoidf_(a[3]) * o[3];
;                     s[4] += sigmoidf_(b[0]) * o[4]; s[5] += sigmoidf_(b[1]) * o[5]; s[6] += sigmoidf_(b[2]) * o[6]; s[7] += sigmoidf_(b[3]) * o[7];
;                     *(u32x4*)(P + (size_t)row * ldc + (col & 1023)) = pack8(s);
;                 }
	v_cvt_pk_bf16_f32 v84, v88, v89
	v_cvt_pk_bf16_f32 v85, v100, v101
	global_store_dwordx4 v[98:99], v[82:85], off offset:256
	v_mov_b32_e32 v114, 0
	s_nop 0
	v_pk_mul_f32 v[82:83], v[74:75], v[224:225] op_sel_hi:[1,0]
	v_exp_f32_e32 v74, v78
	v_exp_f32_e32 v75, v79
	v_lshlrev_b32_e32 v78, 16, v106
	v_and_b32_e32 v79, 0xffff0000, v106
	v_lshlrev_b32_e32 v84, 16, v110
	v_pk_add_f32 v[74:75], v[74:75], 1.0 op_sel_hi:[1,0]
	v_and_b32_e32 v85, 0xffff0000, v110
	s_nop 0
	v_rcp_f32_e32 v75, v75
	s_nop 0
	v_rcp_f32_e32 v74, v74
	s_nop 0
	v_pk_fma_f32 v[74:75], v[74:75], v[78:79], v[84:85]
	v_exp_f32_e32 v78, v80
	v_exp_f32_e32 v79, v81
	v_lshlrev_b32_e32 v80, 16, v107
	v_and_b32_e32 v81, 0xffff0000, v107
	v_lshlrev_b32_e32 v84, 16, v111
	v_pk_add_f32 v[78:79], v[78:79], 1.0 op_sel_hi:[1,0]
	v_and_b32_e32 v85, 0xffff0000, v111
	s_nop 0
	v_rcp_f32_e32 v79, v79
	s_nop 0
	v_rcp_f32_e32 v78, v78
	s_nop 0
	v_pk_fma_f32 v[78:79], v[78:79], v[80:81], v[84:85]
	v_exp_f32_e32 v80, v82
	v_exp_f32_e32 v81, v83
	v_lshlrev_b32_e32 v82, 16, v108
	v_and_b32_e32 v83, 0xffff0000, v108
	v_lshlrev_b32_e32 v84, 16, v112
	v_pk_add_f32 v[80:81], v[80:81], 1.0 op_sel_hi:[1,0]
	v_and_b32_e32 v85, 0xffff0000, v112
	s_nop 0
	v_rcp_f32_e32 v81, v81
	s_nop 0
	v_rcp_f32_e32 v80, v80
	s_nop 0
	v_pk_fma_f32 v[80:81], v[80:81], v[82:83], v[84:85]
	v_lshlrev_b32_e32 v82, 16, v109
	v_and_b32_e32 v83, 0xffff0000, v109
	v_rcp_f32_e32 v77, v77
	v_lshlrev_b32_e32 v84, 16, v113
	v_and_b32_e32 v85, 0xffff0000, v113
	v_rcp_f32_e32 v76, v76
	s_nop 0
	v_pk_fma_f32 v[82:83], v[76:77], v[82:83], v[84:85]
	v_cvt_pk_bf16_f32 v76, v74, v75
	v_cvt_pk_bf16_f32 v77, v78, v79
	v_cvt_pk_bf16_f32 v78, v80, v81
	v_cvt_pk_bf16_f32 v79, v82, v83
	v_lshl_add_u64 v[74:75], v[222:223], 0, v[0:1]
	global_store_dwordx4 v[74:75], v[76:79], off
	s_nop 1
	v_pk_mul_f32 v[76:77], v[66:67], v[224:225] op_sel_hi:[1,0]
	v_exp_f32_e32 v66, v70
	v_exp_f32_e32 v67, v71
	v_lshlrev_b32_e32 v70, 16, v94
	v_and_b32_e32 v71, 0xffff0000, v94
	v_lshlrev_b32_e32 v78, 16, v90
	v_pk_add_f32 v[66:67], v[66:67], 1.0 op_sel_hi:[1,0]
	v_and_b32_e32 v79, 0xffff0000, v90
	s_nop 0
	v_rcp_f32_e32 v67, v67
	s_nop 0
	v_rcp_f32_e32 v66, v66
	s_nop 0
	v_pk_fma_f32 v[66:67], v[66:67], v[70:71], v[78:79]
	v_exp_f32_e32 v70, v72
	v_exp_f32_e32 v71, v73
	v_lshlrev_b32_e32 v72, 16, v95
	v_and_b32_e32 v73, 0xffff0000, v95
	v_lshlrev_b32_e32 v78, 16, v91
	v_pk_add_f32 v[70:71], v[70:71], 1.0 op_sel_hi:[1,0]
	v_and_b32_e32 v79, 0xffff0000, v91
	v_cvt_pk_bf16_f32 v66, v66, v67
	v_rcp_f32_e32 v71, v71
	s_nop 0
	v_rcp_f32_e32 v70, v70
	s_nop 0
	v_pk_fma_f32 v[70:71], v[70:71], v[72:73], v[78:79]
	v_exp_f32_e32 v72, v76
	v_exp_f32_e32 v73, v77
	v_lshlrev_b32_e32 v76, 16, v96
	v_and_b32_e32 v77, 0xffff0000, v96
	v_lshlrev_b32_e32 v78, 16, v92
	v_pk_add_f32 v[72:73], v[72:73], 1.0 op_sel_hi:[1,0]
	v_and_b32_e32 v79, 0xffff0000, v92
	v_cvt_pk_bf16_f32 v67, v70, v71
	v_rcp_f32_e32 v73, v73
	s_nop 0
	v_rcp_f32_e32 v72, v72
	s_nop 0
	v_pk_fma_f32 v[72:73], v[72:73], v[76:77], v[78:79]
	v_lshlrev_b32_e32 v76, 16, v97
	v_and_b32_e32 v77, 0xffff0000, v97
	v_rcp_f32_e32 v69, v69
	v_lshlrev_b32_e32 v78, 16, v93
	v_and_b32_e32 v79, 0xffff0000, v93
	v_rcp_f32_e32 v68, v68
	s_nop 0
	v_pk_fma_f32 v[76:77], v[68:69], v[76:77], v[78:79]
	v_cvt_pk_bf16_f32 v68, v72, v73
	v_cvt_pk_bf16_f32 v69, v76, v77
	global_store_dwordx4 v[74:75], v[66:69], off offset:256
	s_and_b64 vcc, exec, s[4:5]
	s_nop 0
	v_add_u32_e32 v68, 0x80, v218
	v_mov_b64_e32 v[66:67], s[18:19]
	v_mad_i64_i32 v[142:143], s[50:51], v68, s58, v[66:67]
	v_lshl_add_u64 v[66:67], v[216:217], 1, v[142:143]
	global_load_dwordx4 v[122:125], v[66:67], off
	s_cbranch_vccnz .LBB0_1384
	v_lshl_add_u64 v[68:69], v[142:143], 0, v[0:1]
	global_load_dwordx4 v[126:129], v[68:69], off

; DI float sigmoidf_(float x) { return 1.0f / (1.0f + __expf(-x)); }
; DI void unpack8(const u32x4 w, float (&f)[8]) { f[0] = bflo(w.x); f[1] = bfhi(w.x); f[2] = bflo(w.y); f[3] = bfhi(w.y); f[4] = bflo(w.z); f[5] = bfhi(w.z); f[6] = bflo(w.w); f[7] = bfhi(w.w); }
; DI u32x4 pack8(const float (&f)[8]) { u32x4 w; w.x = pk2(f[0], f[1]); w.y = pk2(f[2], f[3]); w.z = pk2(f[4], f[5]); w.w = pk2(f[6], f[7]); return w; }
; DI float rscale(const float* ss, int row) { const unsigned long long v = ((const unsigned long long*)ss)[row]; return rsqrtf((float)v * (1.0f / SS_FIX) * (1.f / 1024.f) + EPS); }
;     __device__ __forceinline__ void operator()(const f32x4 (&acc)[2][2][4][2], const pg8::Unit& u, int wr, int wc, int fr, int fq) const {
;     ...
;                 rc[m] = rscale(ss, row);
;             }
; #pragma unroll
;             for (int m = 0; m < 4; ++m) {
;                 const int row = row0 + ai * pg8::HALF + m * 16;
; #pragma unroll
;                 for (int bj = 0; bj < 2; ++bj) {
;                     const int col = col0 + bj * pg8::HALF;
;                     const f32x4 a = acc[ai][bj][m][0] * rc[m], b = acc[ai][bj][m][1] * rc[m];
;                     float o[8], s[8]; unpack8(ov[m][bj], o); unpack8(sv[m][bj], s);
;                     s[0] += sigmoidf_(a[0]) * o[0]; s[1] += sigmoidf_(a[1]) * o[1]; s[2] += sigmoidf_(a[2]) * o[2]; s[3] += sigmoidf_(a[3]) * o[3];
;                     s[4] += sigmoidf_(b[0]) * o[4]; s[5] += sigmoidf_(b[1]) * o[5]; s[6] += sigmoidf_(b[2]) * o[6]; s[7] += sigmoidf_(b[3]) * o[7];
;                     *(u32x4*)(P + (size_t)row * ldc + (col & 1023)) = pack8(s);
;                 }
.LBB0_1398:
	s_waitcnt vmcnt(0)
	v_ffbh_u32_e32 v144, v137
	v_min_u32_e32 v144, 32, v144
	v_lshlrev_b64 v[136:137], v144, v[136:137]
	v_min_u32_e32 v136, 1, v136
	v_or_b32_e32 v136, v137, v136
	v_cvt_f32_u32_e32 v136, v136
	v_sub_u32_e32 v137, 32, v144
	v_lshlrev_b32_e32 v146, 16, v126
	v_and_b32_e32 v147, 0xffff0000, v126
	v_ldexp_f32 v136, v136, v137
	v_mul_f32_e32 v136, 0x33800000, v136
	v_fmamk_f32 v136, v136, 0x3a800000, v247
	v_cmp_gt_f32_e32 vcc, s59, v136
	v_mul_f32_e32 v137, 0x4b800000, v136
	s_nop 0
	v_cndmask_b32_e32 v136, v136, v137, vcc
	v_rsq_f32_e32 v136, v136
	s_nop 0
	v_mul_f32_e32 v137, 0x45800000, v136
	v_cndmask_b32_e32 v136, v136, v137, vcc
	v_mul_f32_e32 v136, 0xbfb8aa3b, v136
	v_ffbh_u32_e32 v137, v141
	v_min_u32_e32 v137, 32, v137
	v_lshlrev_b64 v[140:141], v137, v[140:141]
	v_min_u32_e32 v140, 1, v140
	v_or_b32_e32 v140, v141, v140
	v_cvt_f32_u32_e32 v140, v140
	v_sub_u32_e32 v137, 32, v137
	v_ldexp_f32 v137, v140, v137
	v_mul_f32_e32 v137, 0x33800000, v137
	v_fmamk_f32 v137, v137, 0x3a800000, v247
	v_cmp_gt_f32_e32 vcc, s59, v137
	v_mul_f32_e32 v140, 0x4b800000, v137
	s_nop 0
	v_cndmask_b32_e32 v137, v137, v140, vcc
	v_rsq_f32_e32 v137, v137
	s_nop 0
	v_mul_f32_e32 v140, 0x45800000, v137
	v_cndmask_b32_e32 v140, v137, v140, vcc
	v_mul_f32_e32 v140, 0xbfb8aa3b, v140
	v_ffbh_u32_e32 v137, v133
	v_min_u32_e32 v137, 32, v137
	v_lshlrev_b64 v[132:133], v137, v[132:133]
	v_min_u32_e32 v132, 1, v132
	v_or_b32_e32 v132, v133, v132
	v_cvt_f32_u32_e32 v132, v132
	v_sub_u32_e32 v133, 32, v137
	v_ldexp_f32 v132, v132, v133
	v_mul_f32_e32 v132, 0x33800000, v132
	v_fmamk_f32 v132, v132, 0x3a800000, v247
	v_cmp_gt_f32_e32 vcc, s59, v132
	v_mul_f32_e32 v133, 0x4b800000, v132
	s_nop 0
	v_cndmask_b32_e32 v132, v132, v133, vcc
	v_rsq_f32_e32 v132, v132
	s_nop 0
	v_mul_f32_e32 v133, 0x45800000, v132
	v_cndmask_b32_e32 v144, v132, v133, vcc
	v_mul_f32_e32 v144, 0xbfb8aa3b, v144
	global_load_dwordx2 v[132:133], v[214:215], off offset:1408
	v_pk_mul_f32 v[62:63], v[62:63], v[144:145] op_sel_hi:[1,0]
	v_pk_mul_f32 v[64:65], v[64:65], v[144:145] op_sel_hi:[1,0]
	v_exp_f32_e32 v148, v62
	v_exp_f32_e32 v149, v63
	v_lshlrev_b32_e32 v62, 16, v122
	v_and_b32_e32 v63, 0xffff0000, v122
	v_pk_add_f32 v[148:149], v[148:149], 1.0 op_sel_hi:[1,0]
	v_exp_f32_e32 v64, v64
	v_exp_f32_e32 v65, v65
	v_pk_mul_f32 v[60:61], v[60:61], v[144:145] op_sel_hi:[1,0]
	v_pk_mul_f32 v[58:59], v[58:59], v[144:145] op_sel_hi:[1,0]
	v_pk_add_f32 v[64:65], v[64:65], 1.0 op_sel_hi:[1,0]
	v_exp_f32_e32 v58, v58
	v_exp_f32_e32 v59, v59
	v_exp_f32_e32 v60, v60
	v_exp_f32_e32 v61, v61
	v_pk_add_f32 v[58:59], v[58:59], 1.0 op_sel_hi:[1,0]
	v_pk_add_f32 v[60:61], v[60:61], 1.0 op_sel_hi:[1,0]
	s_waitcnt vmcnt(0)
	v_ffbh_u32_e32 v137, v133
	v_min_u32_e32 v137, 32, v137
	v_lshlrev_b64 v[132:133], v137, v[132:133]
	v_min_u32_e32 v132, 1, v132
	v_or_b32_e32 v132, v133, v132
	v_cvt_f32_u32_e32 v132, v132
	v_sub_u32_e32 v133, 32, v137
	v_ldexp_f32 v132, v132, v133
	v_mul_f32_e32 v132, 0x33800000, v132
	v_fmamk_f32 v132, v132, 0x3a800000, v247
	v_cmp_gt_f32_e32 vcc, s59, v132
	v_mul_f32_e32 v133, 0x4b800000, v132
	s_nop 0
	v_cndmask_b32_e32 v132, v132, v133, vcc
	v_rsq_f32_e32 v132, v132
	s_nop 0
	v_mul_f32_e32 v133, 0x45800000, v132
	v_cndmask_b32_e32 v132, v132, v133, vcc
	v_mul_f32_e32 v132, 0xbfb8aa3b, v132
	v_rcp_f32_e32 v149, v149
	s_nop 0
	v_rcp_f32_e32 v148, v148
	s_nop 0
	v_pk_fma_f32 v[62:63], v[148:149], v[62:63], v[146:147]
	v_lshlrev_b32_e32 v122, 16, v123
	v_rcp_f32_e32 v65, v65
	v_and_b32_e32 v123, 0xffff0000, v123
	v_lshlrev_b32_e32 v126, 16, v127
	v_and_b32_e32 v127, 0xffff0000, v127
	v_rcp_f32_e32 v64, v64
	s_nop 0
	v_pk_fma_f32 v[64:65], v[64:65], v[122:123], v[126:127]
	v_lshlrev_b32_e32 v122, 16, v124
	v_and_b32_e32 v123, 0xffff0000, v124
	v_lshlrev_b32_e32 v126, 16, v128
	v_and_b32_e32 v127, 0xffff0000, v128
	v_pk_mul_f32 v[54:55], v[54:55], v[144:145] op_sel_hi:[1,0]
	v_pk_mul_f32 v[56:57], v[56:57], v[144:145] op_sel_hi:[1,0]
	v_pk_mul_f32 v[52:53], v[52:53], v[144:145] op_sel_hi:[1,0]
	v_rcp_f32_e32 v59, v59
	v_exp_f32_e32 v52, v52
	v_rcp_f32_e32 v58, v58
	s_nop 0
	v_pk_fma_f32 v[58:59], v[58:59], v[122:123], v[126:127]
	v_lshlrev_b32_e32 v122, 16, v125
	v_and_b32_e32 v123, 0xffff0000, v125
	v_lshlrev_b32_e32 v124, 16, v129
	v_and_b32_e32 v125, 0xffff0000, v129
	v_rcp_f32_e32 v61, v61
	v_exp_f32_e32 v53, v53
	v_pk_mul_f32 v[46:47], v[46:47], v[140:141] op_sel_hi:[1,0]
	v_pk_mul_f32 v[48:49], v[48:49], v[140:141] op_sel_hi:[1,0]
	v_rcp_f32_e32 v60, v60
	s_nop 0
	v_pk_fma_f32 v[122:123], v[60:61], v[122:123], v[124:125]
	v_cvt_pk_bf16_f32 v60, v62, v63
	v_cvt_pk_bf16_f32 v61, v64, v65
	v_cvt_pk_bf16_f32 v62, v58, v59
	v_cvt_pk_bf16_f32 v63, v122, v123
	v_lshl_add_u64 v[58:59], v[142:143], 0, v[0:1]
	global_store_dwordx4 v[58:59], v[60:63], off
	v_pk_add_f32 v[52:53], v[52:53], 1.0 op_sel_hi:[1,0]
	v_pk_mul_f32 v[44:45], v[44:45], v[140:141] op_sel_hi:[1,0]
	v_pk_mul_f32 v[60:61], v[50:51], v[144:145] op_sel_hi:[1,0]
	v_exp_f32_e32 v50, v54
	v_exp_f32_e32 v51, v55
	v_lshlrev_b32_e32 v62, 16, v114
	v_and_b32_e32 v63, 0xffff0000, v114
	v_lshlrev_b32_e32 v54, 16, v118
	v_pk_add_f32 v[50:51], v[50:51], 1.0 op_sel_hi:[1,0]
	v_and_b32_e32 v55, 0xffff0000, v118
	v_exp_f32_e32 v44, v44
	v_rcp_f32_e32 v51, v51
	v_exp_f32_e32 v45, v45
	v_pk_mul_f32 v[38:39], v[38:39], v[140:141] op_sel_hi:[1,0]
	v_pk_mul_f32 v[40:41], v[40:41], v[140:141] op_sel_hi:[1,0]
	v_rcp_f32_e32 v50, v50
	s_nop 0
	v_pk_fma_f32 v[50:51], v[50:51], v[54:55], v[62:63]
	v_exp_f32_e32 v54, v56
	v_exp_f32_e32 v55, v57
	v_lshlrev_b32_e32 v62, 16, v115
	v_and_b32_e32 v63, 0xffff0000, v115
; DI float sigmoidf_(float x) { return 1.0f / (1.0f + __expf(-x)); }
; DI void unpack8(const u32x4 w, float (&f)[8]) { f[0] = bflo(w.x); f[1] = bfhi(w.x); f[2] = bflo(w.y); f[3] = bfhi(w.y); f[4] = bflo(w.z); f[5] = bfhi(w.z); f[6] = bflo(w.w); f[7] = bfhi(w.w); }
; DI u32x4 pack8(const float (&f)[8]) { u32x4 w; w.x = pk2(f[0], f[1]); w.y = pk2(f[2], f[3]); w.z = pk2(f[4], f[5]); w.w = pk2(f[6], f[7]); return w; }
;     __device__ __forceinline__ void operator()(const f32x4 (&acc)[2][2][4][2], const pg8::Unit& u, int wr, int wc, int fr, int fq) const {
;     ...
;             for (int m = 0; m < 4; ++m) {
;                 const int row = row0 + ai * pg8::HALF + m * 16;
; #pragma unroll
;                 for (int bj = 0; bj < 2; ++bj) {
;                     const int col = col0 + bj * pg8::HALF;
;                     const f32x4 a = acc[ai][bj][m][0] * rc[m], b = acc[ai][bj][m][1] * rc[m];
;                     float o[8], s[8]; unpack8(ov[m][bj], o); unpack8(sv[m][bj], s);
;                     s[0] += sigmoidf_(a[0]) * o[0]; s[1] += sigmoidf_(a[1]) * o[1]; s[2] += sigmoidf_(a[2]) * o[2]; s[3] += sigmoidf_(a[3]) * o[3];
;                     s[4] += sigmoidf_(b[0]) * o[4]; s[5] += sigmoidf_(b[1]) * o[5]; s[6] += sigmoidf_(b[2]) * o[6]; s[7] += sigmoidf_(b[3]) * o[7];
;                     *(u32x4*)(P + (size_t)row * ldc + (col & 1023)) = pack8(s);
;                 }
	v_lshlrev_b32_e32 v56, 16, v119
	v_pk_add_f32 v[54:55], v[54:55], 1.0 op_sel_hi:[1,0]
	v_and_b32_e32 v57, 0xffff0000, v119
	v_cvt_pk_bf16_f32 v50, v50, v51
	v_pk_add_f32 v[44:45], v[44:45], 1.0 op_sel_hi:[1,0]
	v_pk_mul_f32 v[36:37], v[36:37], v[140:141] op_sel_hi:[1,0]
	v_rcp_f32_e32 v55, v55
	v_exp_f32_e32 v36, v36
	v_rcp_f32_e32 v54, v54
	s_nop 0
	v_pk_fma_f32 v[54:55], v[54:55], v[56:57], v[62:63]
	v_exp_f32_e32 v56, v60
	v_exp_f32_e32 v57, v61
	v_lshlrev_b32_e32 v62, 16, v116
	v_and_b32_e32 v63, 0xffff0000, v116
	v_lshlrev_b32_e32 v60, 16, v120
	v_pk_add_f32 v[56:57], v[56:57], 1.0 op_sel_hi:[1,0]
	v_and_b32_e32 v61, 0xffff0000, v120
	v_cvt_pk_bf16_f32 v51, v54, v55
	v_exp_f32_e32 v37, v37
	v_pk_mul_f32 v[30:31], v[30:31], v[136:137] op_sel_hi:[1,0]
	v_rcp_f32_e32 v57, v57
	v_pk_add_f32 v[36:37], v[36:37], 1.0 op_sel_hi:[1,0]
	v_pk_mul_f32 v[32:33], v[32:33], v[136:137] op_sel_hi:[1,0]
	v_pk_mul_f32 v[28:29], v[28:29], v[136:137] op_sel_hi:[1,0]
	v_rcp_f32_e32 v56, v56
	s_nop 0
	v_pk_fma_f32 v[56:57], v[56:57], v[60:61], v[62:63]
	v_lshlrev_b32_e32 v60, 16, v121
	v_and_b32_e32 v61, 0xffff0000, v121
	v_rcp_f32_e32 v53, v53
	v_lshlrev_b32_e32 v62, 16, v117
	v_and_b32_e32 v63, 0xffff0000, v117
	v_rcp_f32_e32 v52, v52
	s_nop 0
	v_pk_fma_f32 v[60:61], v[52:53], v[60:61], v[62:63]
	v_cvt_pk_bf16_f32 v52, v56, v57
	v_cvt_pk_bf16_f32 v53, v60, v61
	global_store_dwordx4 v[58:59], v[50:53], off offset:256
	v_exp_f32_e32 v28, v28
	s_nop 1
	v_pk_mul_f32 v[50:51], v[42:43], v[140:141] op_sel_hi:[1,0]
	v_exp_f32_e32 v42, v46
	v_exp_f32_e32 v43, v47
	v_lshlrev_b32_e32 v46, 16, v106
	v_and_b32_e32 v47, 0xffff0000, v106
	v_lshlrev_b32_e32 v52, 16, v110
	v_pk_add_f32 v[42:43], v[42:43], 1.0 op_sel_hi:[1,0]
	v_and_b32_e32 v53, 0xffff0000, v110
	v_exp_f32_e32 v29, v29
	v_pk_mul_f32 v[22:23], v[22:23], v[136:137] op_sel_hi:[1,0]
	v_pk_mul_f32 v[24:25], v[24:25], v[136:137] op_sel_hi:[1,0]
	v_rcp_f32_e32 v43, v43
	v_pk_add_f32 v[28:29], v[28:29], 1.0 op_sel_hi:[1,0]
	v_pk_mul_f32 v[20:21], v[20:21], v[136:137] op_sel_hi:[1,0]
	v_pk_mul_f32 v[14:15], v[14:15], v[132:133] op_sel_hi:[1,0]
	v_rcp_f32_e32 v42, v42
	s_nop 0
	v_pk_fma_f32 v[42:43], v[42:43], v[46:47], v[52:53]
	v_exp_f32_e32 v46, v48
	v_exp_f32_e32 v47, v49
	v_lshlrev_b32_e32 v48, 16, v107
	v_and_b32_e32 v49, 0xffff0000, v107
	v_lshlrev_b32_e32 v52, 16, v111
	v_pk_add_f32 v[46:47], v[46:47], 1.0 op_sel_hi:[1,0]
	v_and_b32_e32 v53, 0xffff0000, v111
	v_exp_f32_e32 v20, v20
	v_rcp_f32_e32 v47, v47
	v_exp_f32_e32 v21, v21
	v_pk_mul_f32 v[16:17], v[16:17], v[132:133] op_sel_hi:[1,0]
	v_pk_mul_f32 v[12:13], v[12:13], v[132:133] op_sel_hi:[1,0]
	v_rcp_f32_e32 v46, v46
	s_nop 0
	v_pk_fma_f32 v[46:47], v[46:47], v[48:49], v[52:53]
	v_exp_f32_e32 v48, v50
	v_exp_f32_e32 v49, v51
	v_lshlrev_b32_e32 v50, 16, v108
	v_and_b32_e32 v51, 0xffff0000, v108
	v_lshlrev_b32_e32 v52, 16, v112
	v_pk_add_f32 v[48:49], v[48:49], 1.0 op_sel_hi:[1,0]
	v_and_b32_e32 v53, 0xffff0000, v112
	v_pk_add_f32 v[20:21], v[20:21], 1.0 op_sel_hi:[1,0]
	v_rcp_f32_e32 v49, v49
	v_exp_f32_e32 v12, v12
	v_exp_f32_e32 v13, v13
	v_pk_mul_f32 v[6:7], v[6:7], v[132:133] op_sel_hi:[1,0]
	v_rcp_f32_e32 v48, v48
	s_nop 0
	v_pk_fma_f32 v[48:49], v[48:49], v[50:51], v[52:53]
	v_lshlrev_b32_e32 v50, 16, v109
	v_and_b32_e32 v51, 0xffff0000, v109
	v_rcp_f32_e32 v45, v45
	v_lshlrev_b32_e32 v52, 16, v113
	v_and_b32_e32 v53, 0xffff0000, v113
	v_pk_add_f32 v[12:13], v[12:13], 1.0 op_sel_hi:[1,0]
	v_rcp_f32_e32 v44, v44
	s_nop 0
	v_pk_fma_f32 v[50:51], v[44:45], v[50:51], v[52:53]
	v_cvt_pk_bf16_f32 v44, v42, v43
	v_cvt_pk_bf16_f32 v45, v46, v47
	v_cvt_pk_bf16_f32 v46, v48, v49
	v_cvt_pk_bf16_f32 v47, v50, v51
	v_lshl_add_u64 v[42:43], v[138:139], 0, v[0:1]
	global_store_dwordx4 v[42:43], v[44:47], off
	v_pk_mul_f32 v[8:9], v[8:9], v[132:133] op_sel_hi:[1,0]
	v_pk_mul_f32 v[4:5], v[4:5], v[132:133] op_sel_hi:[1,0]
	v_pk_mul_f32 v[44:45], v[34:35], v[140:141] op_sel_hi:[1,0]
	v_exp_f32_e32 v34, v38
	v_exp_f32_e32 v35, v39
	v_lshlrev_b32_e32 v38, 16, v102
	v_and_b32_e32 v39, 0xffff0000, v102
	v_lshlrev_b32_e32 v46, 16, v98
	v_pk_add_f32 v[34:35], v[34:35], 1.0 op_sel_hi:[1,0]
	v_and_b32_e32 v47, 0xffff0000, v98
	s_nop 0
	v_rcp_f32_e32 v35, v35
	s_nop 0
	v_rcp_f32_e32 v34, v34
	s_nop 0
	v_pk_fma_f32 v[34:35], v[34:35], v[38:39], v[46:47]
	v_exp_f32_e32 v38, v40
	v_exp_f32_e32 v39, v41
	v_lshlrev_b32_e32 v40, 16, v103
	v_and_b32_e32 v41, 0xffff0000, v103
	v_lshlrev_b32_e32 v46, 16, v99
	v_pk_add_f32 v[38:39], v[38:39], 1.0 op_sel_hi:[1,0]
	v_and_b32_e32 v47, 0xffff0000, v99
	v_cvt_pk_bf16_f32 v34, v34, v35
	v_rcp_f32_e32 v39, v39
	s_nop 0
	v_rcp_f32_e32 v38, v38
	s_nop 0
	v_pk_fma_f32 v[38:39], v[38:39], v[40:41], v[46:47]
	v_exp_f32_e32 v40, v44
	v_exp_f32_e32 v41, v45
	v_lshlrev_b32_e32 v44, 16, v104
	v_and_b32_e32 v45, 0xffff0000, v104
	v_lshlrev_b32_e32 v46, 16, v100
	v_pk_add_f32 v[40:41], v[40:41], 1.0 op_sel_hi:[1,0]
	v_and_b32_e32 v47, 0xffff0000, v100
	v_cvt_pk_bf16_f32 v35, v38, v39
	v_rcp_f32_e32 v41, v41
	s_nop 0
	v_rcp_f32_e32 v40, v40
	s_nop 0
	v_pk_fma_f32 v[40:41], v[40:41], v[44:45], v[46:47]
	v_lshlrev_b32_e32 v44, 16, v105
	v_and_b32_e32 v45, 0xffff0000, v105
	v_rcp_f32_e32 v37, v37
	v_lshlrev_b32_e32 v46, 16, v101
	v_and_b32_e32 v47, 0xffff0000, v101
	v_rcp_f32_e32 v36, v36
	s_nop 0
	v_pk_fma_f32 v[44:45], v[36:37], v[44:45], v[46:47]
	v_cvt_pk_bf16_f32 v36, v40, v41
	v_cvt_pk_bf16_f32 v37, v44, v45
	global_store_dwordx4 v[42:43], v[34:37], off offset:256
	s_nop 1
	v_pk_mul_f32 v[34:35], v[26:27], v[136:137] op_sel_hi:[1,0]
	v_exp_f32_e32 v26, v30
	v_exp_f32_e32 v27, v31
	v_lshlrev_b32_e32 v30, 16, v90
	v_and_b32_e32 v31, 0xffff0000, v90
; DI float sigmoidf_(float x) { return 1.0f / (1.0f + __expf(-x)); }
; DI void unpack8(const u32x4 w, float (&f)[8]) { f[0] = bflo(w.x); f[1] = bfhi(w.x); f[2] = bflo(w.y); f[3] = bfhi(w.y); f[4] = bflo(w.z); f[5] = bfhi(w.z); f[6] = bflo(w.w); f[7] = bfhi(w.w); }
; DI u32x4 pack8(const float (&f)[8]) { u32x4 w; w.x = pk2(f[0], f[1]); w.y = pk2(f[2], f[3]); w.z = pk2(f[4], f[5]); w.w = pk2(f[6], f[7]); return w; }
; #define PG8_BAR __builtin_amdgcn_s_barrier()
; template <class Epi, class Sched>
; __device__ __forceinline__ void gemm_phase(PG8_LAS unsigned char* lds, const Gemm g, const Sched& S, const Epi& E) {
;     ...
;         if (wr == 0) PG8_BAR;
;         E(acc, cur, wr, wc, fr, fq);
;         if (!has_next) break;
; #pragma unroll
;         for (int a = 0; a < 2; ++a)
; #pragma unroll
;             for (int b = 0; b < 2; ++b)
; #pragma unroll
;                 for (int m = 0; m < 4; ++m)
; #pragma unroll
;                     for (int n = 0; n < 2; ++n) acc[a][b][m][n] = (f32x4){0.f, 0.f, 0.f, 0.f};
;         cur = nxt; cA = nA; cB = nB; ++ui;
;         if (wr == 1) PG8_BAR;
;     __device__ __forceinline__ void operator()(const f32x4 (&acc)[2][2][4][2], const pg8::Unit& u, int wr, int wc, int fr, int fq) const {
;     ...
;             for (int m = 0; m < 4; ++m) {
;                 const int row = row0 + ai * pg8::HALF + m * 16;
; #pragma unroll
;                 for (int bj = 0; bj < 2; ++bj) {
;                     const int col = col0 + bj * pg8::HALF;
;                     const f32x4 a = acc[ai][bj][m][0] * rc[m], b = acc[ai][bj][m][1] * rc[m];
;                     float o[8], s[8]; unpack8(ov[m][bj], o); unpack8(sv[m][bj], s);
;                     s[0] += sigmoidf_(a[0]) * o[0]; s[1] += sigmoidf_(a[1]) * o[1]; s[2] += sigmoidf_(a[2]) * o[2]; s[3] += sigmoidf_(a[3]) * o[3];
;                     s[4] += sigmoidf_(b[0]) * o[4]; s[5] += sigmoidf_(b[1]) * o[5]; s[6] += sigmoidf_(b[2]) * o[6]; s[7] += sigmoidf_(b[3]) * o[7];
;                     *(u32x4*)(P + (size_t)row * ldc + (col & 1023)) = pack8(s);
;                 }
;             }
	v_lshlrev_b32_e32 v36, 16, v94
	v_pk_add_f32 v[26:27], v[26:27], 1.0 op_sel_hi:[1,0]
	v_and_b32_e32 v37, 0xffff0000, v94
	s_nop 0
	v_rcp_f32_e32 v27, v27
	s_nop 0
	v_rcp_f32_e32 v26, v26
	s_nop 0
	v_pk_fma_f32 v[26:27], v[26:27], v[30:31], v[36:37]
	v_exp_f32_e32 v30, v32
	v_exp_f32_e32 v31, v33
	v_lshlrev_b32_e32 v32, 16, v91
	v_and_b32_e32 v33, 0xffff0000, v91
	v_lshlrev_b32_e32 v36, 16, v95
	v_pk_add_f32 v[30:31], v[30:31], 1.0 op_sel_hi:[1,0]
	v_and_b32_e32 v37, 0xffff0000, v95
	s_nop 0
	v_rcp_f32_e32 v31, v31
	s_nop 0
	v_rcp_f32_e32 v30, v30
	s_nop 0
	v_pk_fma_f32 v[30:31], v[30:31], v[32:33], v[36:37]
	v_exp_f32_e32 v32, v34
	v_exp_f32_e32 v33, v35
	v_lshlrev_b32_e32 v34, 16, v92
	v_and_b32_e32 v35, 0xffff0000, v92
	v_lshlrev_b32_e32 v36, 16, v96
	v_pk_add_f32 v[32:33], v[32:33], 1.0 op_sel_hi:[1,0]
	v_and_b32_e32 v37, 0xffff0000, v96
	s_nop 0
	v_rcp_f32_e32 v33, v33
	s_nop 0
	v_rcp_f32_e32 v32, v32
	s_nop 0
	v_pk_fma_f32 v[32:33], v[32:33], v[34:35], v[36:37]
	v_lshlrev_b32_e32 v34, 16, v93
	v_and_b32_e32 v35, 0xffff0000, v93
	v_rcp_f32_e32 v29, v29
	v_lshlrev_b32_e32 v36, 16, v97
	v_and_b32_e32 v37, 0xffff0000, v97
	v_rcp_f32_e32 v28, v28
	s_nop 0
	v_pk_fma_f32 v[34:35], v[28:29], v[34:35], v[36:37]
	v_cvt_pk_bf16_f32 v28, v26, v27
	v_cvt_pk_bf16_f32 v29, v30, v31
	v_cvt_pk_bf16_f32 v30, v32, v33
	v_cvt_pk_bf16_f32 v31, v34, v35
	v_lshl_add_u64 v[26:27], v[134:135], 0, v[0:1]
	global_store_dwordx4 v[26:27], v[28:31], off
	s_nop 1
	v_pk_mul_f32 v[28:29], v[18:19], v[136:137] op_sel_hi:[1,0]
	v_exp_f32_e32 v18, v22
	v_exp_f32_e32 v19, v23
	v_lshlrev_b32_e32 v22, 16, v86
	v_and_b32_e32 v23, 0xffff0000, v86
	v_lshlrev_b32_e32 v30, 16, v82
	v_pk_add_f32 v[18:19], v[18:19], 1.0 op_sel_hi:[1,0]
	v_and_b32_e32 v31, 0xffff0000, v82
	s_nop 0
	v_rcp_f32_e32 v19, v19
	s_nop 0
	v_rcp_f32_e32 v18, v18
	s_nop 0
	v_pk_fma_f32 v[18:19], v[18:19], v[22:23], v[30:31]
	v_exp_f32_e32 v22, v24
	v_exp_f32_e32 v23, v25
	v_lshlrev_b32_e32 v24, 16, v87
	v_and_b32_e32 v25, 0xffff0000, v87
	v_lshlrev_b32_e32 v30, 16, v83
	v_pk_add_f32 v[22:23], v[22:23], 1.0 op_sel_hi:[1,0]
	v_and_b32_e32 v31, 0xffff0000, v83
	v_cvt_pk_bf16_f32 v18, v18, v19
	v_rcp_f32_e32 v23, v23
	s_nop 0
	v_rcp_f32_e32 v22, v22
	s_nop 0
	v_pk_fma_f32 v[22:23], v[22:23], v[24:25], v[30:31]
	v_exp_f32_e32 v24, v28
	v_exp_f32_e32 v25, v29
	v_lshlrev_b32_e32 v28, 16, v88
	v_and_b32_e32 v29, 0xffff0000, v88
	v_lshlrev_b32_e32 v30, 16, v84
	v_pk_add_f32 v[24:25], v[24:25], 1.0 op_sel_hi:[1,0]
	v_and_b32_e32 v31, 0xffff0000, v84
	v_cvt_pk_bf16_f32 v19, v22, v23
	v_rcp_f32_e32 v25, v25
	s_nop 0
	v_rcp_f32_e32 v24, v24
	s_nop 0
	v_pk_fma_f32 v[24:25], v[24:25], v[28:29], v[30:31]
	v_lshlrev_b32_e32 v28, 16, v89
	v_and_b32_e32 v29, 0xffff0000, v89
	v_rcp_f32_e32 v21, v21
	v_lshlrev_b32_e32 v30, 16, v85
	v_and_b32_e32 v31, 0xffff0000, v85
	v_rcp_f32_e32 v20, v20
	s_nop 0
	v_pk_fma_f32 v[28:29], v[20:21], v[28:29], v[30:31]
	v_cvt_pk_bf16_f32 v20, v24, v25
	v_cvt_pk_bf16_f32 v21, v28, v29
	global_store_dwordx4 v[26:27], v[18:21], off offset:256
	s_nop 1
	v_pk_mul_f32 v[18:19], v[10:11], v[132:133] op_sel_hi:[1,0]
	v_exp_f32_e32 v10, v14
	v_exp_f32_e32 v11, v15
	v_lshlrev_b32_e32 v14, 16, v74
	v_and_b32_e32 v15, 0xffff0000, v74
	v_lshlrev_b32_e32 v20, 16, v78
	v_pk_add_f32 v[10:11], v[10:11], 1.0 op_sel_hi:[1,0]
	v_and_b32_e32 v21, 0xffff0000, v78
	s_nop 0
	v_rcp_f32_e32 v11, v11
	s_nop 0
	v_rcp_f32_e32 v10, v10
	s_nop 0
	v_pk_fma_f32 v[10:11], v[10:11], v[14:15], v[20:21]
	v_exp_f32_e32 v14, v16
	v_exp_f32_e32 v15, v17
	v_lshlrev_b32_e32 v16, 16, v75
	v_and_b32_e32 v17, 0xffff0000, v75
	v_lshlrev_b32_e32 v20, 16, v79
	v_pk_add_f32 v[14:15], v[14:15], 1.0 op_sel_hi:[1,0]
	v_and_b32_e32 v21, 0xffff0000, v79
	s_nop 0
	v_rcp_f32_e32 v15, v15
	s_nop 0
	v_rcp_f32_e32 v14, v14
	s_nop 0
	v_pk_fma_f32 v[14:15], v[14:15], v[16:17], v[20:21]
	v_exp_f32_e32 v16, v18
	v_exp_f32_e32 v17, v19
	v_lshlrev_b32_e32 v18, 16, v76
	v_and_b32_e32 v19, 0xffff0000, v76
	v_lshlrev_b32_e32 v20, 16, v80
	v_pk_add_f32 v[16:17], v[16:17], 1.0 op_sel_hi:[1,0]
	v_and_b32_e32 v21, 0xffff0000, v80
	s_nop 0
	v_rcp_f32_e32 v17, v17
	s_nop 0
	v_rcp_f32_e32 v16, v16
	s_nop 0
	v_pk_fma_f32 v[16:17], v[16:17], v[18:19], v[20:21]
	v_lshlrev_b32_e32 v18, 16, v77
	v_and_b32_e32 v19, 0xffff0000, v77
	v_rcp_f32_e32 v13, v13
	v_lshlrev_b32_e32 v20, 16, v81
	v_and_b32_e32 v21, 0xffff0000, v81
	v_rcp_f32_e32 v12, v12
	s_nop 0
	v_pk_fma_f32 v[18:19], v[12:13], v[18:19], v[20:21]
	v_cvt_pk_bf16_f32 v12, v10, v11
	v_cvt_pk_bf16_f32 v13, v14, v15
	v_cvt_pk_bf16_f32 v14, v16, v17
	v_cvt_pk_bf16_f32 v15, v18, v19
	v_lshl_add_u64 v[10:11], v[130:131], 0, v[0:1]
	v_mov_b32_e32 v0, v6
	global_store_dwordx4 v[10:11], v[12:15], off
	v_lshlrev_b32_e32 v6, 16, v70
	s_nop 0
	v_pk_mul_f32 v[12:13], v[2:3], v[132:133] op_sel_hi:[1,0]
	v_exp_f32_e32 v2, v0
	v_exp_f32_e32 v3, v7
	v_and_b32_e32 v7, 0xffff0000, v70
	v_lshlrev_b32_e32 v14, 16, v66
	v_and_b32_e32 v15, 0xffff0000, v66
	v_pk_add_f32 v[2:3], v[2:3], 1.0 op_sel_hi:[1,0]
	s_nop 0
	s_nop 0
	v_rcp_f32_e32 v3, v3
	s_nop 0
	v_rcp_f32_e32 v2, v2
	s_nop 0
	v_pk_fma_f32 v[2:3], v[2:3], v[6:7], v[14:15]
	v_exp_f32_e32 v6, v8
	v_exp_f32_e32 v7, v9
	v_lshlrev_b32_e32 v8, 16, v71
	v_and_b32_e32 v9, 0xffff0000, v71
	v_lshlrev_b32_e32 v14, 16, v67
	v_pk_add_f32 v[6:7], v[6:7], 1.0 op_sel_hi:[1,0]
	v_and_b32_e32 v15, 0xffff0000, v67
	v_cvt_pk_bf16_f32 v2, v2, v3
	v_rcp_f32_e32 v7, v7
	s_nop 0
	v_rcp_f32_e32 v6, v6
	s_nop 0
	v_pk_fma_f32 v[6:7], v[6:7], v[8:9], v[14:15]
	v_exp_f32_e32 v8, v12
	v_exp_f32_e32 v9, v13
	v_lshlrev_b32_e32 v12, 16, v72
	v_and_b32_e32 v13, 0xffff0000, v72
	v_lshlrev_b32_e32 v14, 16, v68
	v_pk_add_f32 v[8:9], v[8:9], 1.0 op_sel_hi:[1,0]
	v_and_b32_e32 v15, 0xffff0000, v68
	v_cvt_pk_bf16_f32 v3, v6, v7
	v_rcp_f32_e32 v9, v9
	s_nop 0
	v_rcp_f32_e32 v8, v8
	v_exp_f32_e32 v4, v4
	v_exp_f32_e32 v5, v5
	v_pk_fma_f32 v[8:9], v[8:9], v[12:13], v[14:15]
	v_lshlrev_b32_e32 v12, 16, v73
	v_and_b32_e32 v13, 0xffff0000, v73
	v_pk_add_f32 v[4:5], v[4:5], 1.0 op_sel_hi:[1,0]
	v_lshlrev_b32_e32 v14, 16, v69
	v_and_b32_e32 v15, 0xffff0000, v69
	v_rcp_f32_e32 v5, v5
	s_mov_b64 s[4:5], -1
	v_rcp_f32_e32 v4, v4
	s_nop 0
	v_pk_fma_f32 v[12:13], v[4:5], v[12:13], v[14:15]
	v_cvt_pk_bf16_f32 v4, v8, v9
	v_cvt_pk_bf16_f32 v5, v12, v13
	s_and_b64 vcc, exec, s[40:41]
	global_store_dwordx4 v[10:11], v[2:5], off offset:256
	s_cbranch_vccnz .LBB0_1350
	s_andn2_b64 vcc, exec, s[16:17]
	s_cbranch_vccnz .LBB0_1349
	s_barrier
	s_branch .LBB0_1349
